# v11 + grid barrier: non-master blocks poll the top-level generation word directly instead of waiting for the per-XCD release
# speedup vs baseline: 1.0940x; 1.0127x over previous
.LBB0_1900:
	s_or_b64 exec, exec, s[20:21]
	v_cvt_f32_u32_e32 v4, v2
	s_waitcnt vmcnt(0)
	v_readfirstlane_b32 s20, v3
	v_sub_u32_e32 v3, 0, v2
	v_rcp_iflag_f32_e32 v4, v4
	v_add_u32_e32 v5, s20, v1
	v_mul_f32_e32 v4, 0x4f7ffffe, v4
	v_cvt_u32_f32_e32 v4, v4
	v_mul_lo_u32 v1, v3, v4
	v_mul_hi_u32 v1, v4, v1
	v_add_u32_e32 v1, v4, v1
	v_mul_hi_u32 v1, v5, v1
	v_mul_lo_u32 v3, v1, v2
	v_sub_u32_e32 v3, v5, v3
	v_add_u32_e32 v4, 1, v1
	v_cmp_ge_u32_e32 vcc, v3, v2
	s_nop 1
	v_cndmask_b32_e32 v1, v1, v4, vcc
	v_sub_u32_e32 v4, v3, v2
	v_cndmask_b32_e32 v3, v3, v4, vcc
	v_add_u32_e32 v4, 1, v1
	v_cmp_ge_u32_e32 vcc, v3, v2
	v_add_u32_e32 v3, 1, v5
	s_nop 0
	v_cndmask_b32_e32 v1, v1, v4, vcc
	v_mul_lo_u32 v4, v2, v1
	v_add_u32_e32 v2, v4, v2
	v_cmp_ne_u32_e32 vcc, v3, v2
	s_and_saveexec_b64 s[20:21], vcc
	s_xor_b64 s[20:21], exec, s[20:21]
	s_cbranch_execz .LBB0_1914
	v_readlane_b32 s24, v233, 40
	v_readlane_b32 s25, v233, 41
	s_waitcnt lgkmcnt(0)
	s_nop 3
	global_load_dword v0, v33, s[24:25] sc1
	s_waitcnt vmcnt(0)
	v_cmp_eq_u32_e32 vcc, v0, v1
	s_and_saveexec_b64 s[28:29], vcc
	s_cbranch_execz .LBB0_1913
	s_mov_b32 s24, 1
	s_mov_b64 s[36:37], 0
	s_branch .LBB0_1904

.LBB0_1906:
	v_readlane_b32 s30, v233, 40
	v_readlane_b32 s31, v233, 41
	s_add_i32 s24, s24, 1
	s_mov_b64 s[42:43], -1
	s_nop 2
	global_load_dword v0, v33, s[30:31] sc1
	s_waitcnt vmcnt(0)
	v_cmp_ne_u32_e32 vcc, v0, v1
	s_orn2_b64 s[40:41], vcc, exec
	s_branch .LBB0_1903
